# group-barrier acquire invalidate issued right after the arrival (overlaps the wait; all waves are parked until release) - on top of v63
# speedup vs baseline: 1.0029x; 1.0029x over previous
.Lmy_gchk_4:
	s_mov_b32 s2, -1
	s_nop 0
	v_mbcnt_lo_u32_b32 v0, s2, 0
	v_mbcnt_hi_u32_b32 v0, s2, v0
	s_nop 0
	v_cmp_eq_u32_e32 vcc, 0, v0
	s_and_saveexec_b64 s[16:17], vcc
	s_cbranch_execz .LBB0_905
	s_cmp_lg_u32 s101, 1
	s_cbranch_scc1 .Lmy_gfull_4
	v_readlane_b32 s2, v253, 37
	v_readlane_b32 s3, v250, 7
	v_readlane_b32 s8, v250, 0
	v_readlane_b32 s9, v250, 1
	s_lshl_b32 s2, s2, 12
	s_add_i32 s2, s2, 0x4000
	s_and_b32 s3, s3, 63
	s_lshl_b32 s3, s3, 6
	s_add_i32 s2, s2, s3
	s_add_u32 s8, s8, 0x70000
	s_addc_u32 s9, s9, 0
	v_mov_b32_e32 v0, s2
	v_mov_b32_e32 v1, 1
	s_waitcnt vmcnt(0) lgkmcnt(0)
	global_atomic_add v0, v1, s[8:9]
	buffer_inv sc1
	s_mov_b32 s2, 0
.Lmy_gspin_4:
	global_load_dword v2, v0, s[8:9] sc1
	s_waitcnt vmcnt(0)
	v_readfirstlane_b32 s3, v2
	s_cmp_ge_u32 s3, 4
	s_cbranch_scc1 .Lmy_gdone_4
	s_sleep 1
	s_add_i32 s2, s2, 1
	s_cmp_lt_u32 s2, 0x4000
	s_cbranch_scc1 .Lmy_gspin_4
.Lmy_gdone_4:
	s_branch .LBB0_905
.Lmy_gfull_4:
	v_readlane_b32 s2, v252, 30
	s_waitcnt vmcnt(0) expcnt(0) lgkmcnt(0)
	s_nop 0
	v_mov_b32_e32 v0, s2
	ds_read_b32 v2, v0
	v_readlane_b32 s2, v252, 31
	s_waitcnt lgkmcnt(0)
	v_cmp_ne_u32_e32 vcc, 0, v2
	v_mov_b32_e32 v0, s2
	ds_read_b32 v0, v0
	s_cbranch_vccnz .LBB0_869
	v_readlane_b32 s8, v250, 4
	v_readlane_b32 s9, v250, 5
	s_load_dwordx2 s[2:3], s[8:9], 0x4
	s_waitcnt lgkmcnt(0)
	s_mul_i32 s2, s2, s94
	s_mul_i32 s2, s2, s3
	s_mov_b32 s3, 1
	s_branch .LBB0_857

.Lmy_gchk_7:
	s_mov_b32 s0, -1
	s_nop 0
	v_mbcnt_lo_u32_b32 v0, s0, 0
	v_mbcnt_hi_u32_b32 v0, s0, v0
	s_nop 0
	v_cmp_eq_u32_e32 vcc, 0, v0
	s_and_saveexec_b64 s[18:19], vcc
	s_cbranch_execz .LBB0_1297
	s_cmp_lg_u32 s101, 1
	s_cbranch_scc1 .Lmy_gfull_7
	v_readlane_b32 s2, v253, 37
	v_readlane_b32 s3, v250, 7
	v_readlane_b32 s8, v250, 0
	v_readlane_b32 s9, v250, 1
	s_lshl_b32 s2, s2, 12
	s_add_i32 s2, s2, 0x7000
	s_and_b32 s3, s3, 63
	s_lshl_b32 s3, s3, 6
	s_add_i32 s2, s2, s3
	s_add_u32 s8, s8, 0x70000
	s_addc_u32 s9, s9, 0
	v_mov_b32_e32 v0, s2
	v_mov_b32_e32 v1, 1
	s_waitcnt vmcnt(0) lgkmcnt(0)
	global_atomic_add v0, v1, s[8:9]
	buffer_inv sc1
	s_mov_b32 s2, 0
.Lmy_gspin_7:
	global_load_dword v2, v0, s[8:9] sc1
	s_waitcnt vmcnt(0)
	v_readfirstlane_b32 s3, v2
	s_cmp_ge_u32 s3, 4
	s_cbranch_scc1 .Lmy_gdone_7
	s_sleep 1
	s_add_i32 s2, s2, 1
	s_cmp_lt_u32 s2, 0x4000
	s_cbranch_scc1 .Lmy_gspin_7
.Lmy_gdone_7:
	s_branch .LBB0_1297
.Lmy_gfull_7:
	v_readlane_b32 s0, v252, 30
	s_waitcnt vmcnt(0) expcnt(0) lgkmcnt(0)
	s_nop 0
	v_mov_b32_e32 v0, s0
	ds_read_b32 v2, v0
	v_readlane_b32 s0, v252, 31
	s_waitcnt lgkmcnt(0)
	v_cmp_ne_u32_e32 vcc, 0, v2
	v_mov_b32_e32 v0, s0
	ds_read_b32 v0, v0
	s_cbranch_vccnz .LBB0_1261
	v_readlane_b32 s8, v250, 4
	v_readlane_b32 s9, v250, 5
	s_load_dwordx2 s[2:3], s[8:9], 0x4
	s_waitcnt lgkmcnt(0)
	s_mul_i32 s0, s2, s94
	s_mul_i32 s0, s0, s3
	s_mov_b32 s2, 1
	s_branch .LBB0_1249

.Lmy_gchk_0:
	s_mov_b32 s2, -1
	s_nop 0
	v_mbcnt_lo_u32_b32 v0, s2, 0
	v_mbcnt_hi_u32_b32 v0, s2, v0
	s_nop 0
	v_cmp_eq_u32_e32 vcc, 0, v0
	s_and_saveexec_b64 s[16:17], vcc
	s_cbranch_execz .LBB0_1954
	s_cmp_lg_u32 s101, 1
	s_cbranch_scc1 .Lmy_gfull_0
	v_readlane_b32 s2, v253, 37
	v_readlane_b32 s3, v250, 7
	v_readlane_b32 s8, v250, 0
	v_readlane_b32 s9, v250, 1
	s_lshl_b32 s2, s2, 12
	s_add_i32 s2, s2, 0x0
	s_and_b32 s3, s3, 63
	s_lshl_b32 s3, s3, 6
	s_add_i32 s2, s2, s3
	s_add_u32 s8, s8, 0x70000
	s_addc_u32 s9, s9, 0
	v_mov_b32_e32 v0, s2
	v_mov_b32_e32 v1, 1
	s_waitcnt vmcnt(0) lgkmcnt(0)
	global_atomic_add v0, v1, s[8:9]
	buffer_inv sc1
	s_mov_b32 s2, 0
.Lmy_gspin_0:
	global_load_dword v2, v0, s[8:9] sc1
	s_waitcnt vmcnt(0)
	v_readfirstlane_b32 s3, v2
	s_cmp_ge_u32 s3, 4
	s_cbranch_scc1 .Lmy_gdone_0
	s_sleep 1
	s_add_i32 s2, s2, 1
	s_cmp_lt_u32 s2, 0x4000
	s_cbranch_scc1 .Lmy_gspin_0
.Lmy_gdone_0:
	s_branch .LBB0_1954
.Lmy_gfull_0:
	v_readlane_b32 s2, v252, 30
	s_waitcnt vmcnt(0) expcnt(0) lgkmcnt(0)
	s_nop 0
	v_mov_b32_e32 v0, s2
	ds_read_b32 v2, v0
	v_readlane_b32 s2, v252, 31
	s_waitcnt lgkmcnt(0)
	v_cmp_ne_u32_e32 vcc, 0, v2
	v_mov_b32_e32 v0, s2
	ds_read_b32 v0, v0
	s_cbranch_vccnz .LBB0_1918
	v_readlane_b32 s8, v250, 4
	v_readlane_b32 s9, v250, 5
	s_load_dwordx2 s[2:3], s[8:9], 0x4
	s_waitcnt lgkmcnt(0)
	s_mul_i32 s2, s2, s94
	s_mul_i32 s2, s2, s3
	s_mov_b32 s3, 1
	s_branch .LBB0_1906

.Lmy_gchk_3:
	s_mov_b32 s2, -1
	s_nop 0
	v_mbcnt_lo_u32_b32 v0, s2, 0
	v_mbcnt_hi_u32_b32 v0, s2, v0
	s_nop 0
	v_cmp_eq_u32_e32 vcc, 0, v0
	s_and_saveexec_b64 s[16:17], vcc
	s_cbranch_execz .LBB0_2032
	s_cmp_lg_u32 s101, 1
	s_cbranch_scc1 .Lmy_gfull_3
	v_readlane_b32 s100, v253, 37
	v_readlane_b32 s3, v250, 7
	v_readlane_b32 s8, v250, 0
	v_readlane_b32 s9, v250, 1
	s_lshl_b32 s12, s100, 12
	s_add_i32 s2, s12, 0x3000
	s_and_b32 s13, s3, 63
	s_lshl_b32 s13, s13, 6
	s_add_i32 s2, s2, s13
	s_add_u32 s8, s8, 0x70000
	s_addc_u32 s9, s9, 0
	v_mov_b32_e32 v0, s2
	v_mov_b32_e32 v1, 1
	s_waitcnt vmcnt(0) lgkmcnt(0)
	global_atomic_add v0, v1, s[8:9]
	buffer_inv sc1
	s_mov_b32 s2, 0

.Lmy_g3_pspin:
	global_load_dword v2, v0, s[8:9] sc1
	s_waitcnt vmcnt(0)
	v_cmp_gt_u32_e32 vcc, 4, v2
	s_cmp_eq_u64 vcc, 0
	s_cbranch_scc1 .Lmy_gdone_3
	s_sleep 8
	s_add_i32 s100, s100, 1
	s_cmp_lt_u32 s100, 0x1000
	s_cbranch_scc1 .Lmy_g3_pspin
.Lmy_gdone_3:
	s_branch .LBB0_2032
.Lmy_gfull_3:
	v_readlane_b32 s2, v252, 30
	s_waitcnt vmcnt(0) expcnt(0) lgkmcnt(0)
	s_nop 0
	v_mov_b32_e32 v0, s2
	ds_read_b32 v2, v0
	v_readlane_b32 s2, v252, 31
	s_waitcnt lgkmcnt(0)
	v_cmp_ne_u32_e32 vcc, 0, v2
	v_mov_b32_e32 v0, s2
	ds_read_b32 v0, v0
	s_cbranch_vccnz .LBB0_1996
	v_readlane_b32 s8, v250, 4
	v_readlane_b32 s9, v250, 5
	s_load_dwordx2 s[2:3], s[8:9], 0x4
	s_waitcnt lgkmcnt(0)
	s_mul_i32 s2, s2, s94
	s_mul_i32 s2, s2, s3
	s_mov_b32 s3, 1
	s_branch .LBB0_1984

.Lmy_gchk_5:
	s_mov_b32 s2, -1
	s_nop 0
	v_mbcnt_lo_u32_b32 v0, s2, 0
	v_mbcnt_hi_u32_b32 v0, s2, v0
	s_nop 0
	v_cmp_eq_u32_e32 vcc, 0, v0
	s_and_saveexec_b64 s[16:17], vcc
	s_cbranch_execz .LBB0_2218
	s_cmp_lg_u32 s101, 1
	s_cbranch_scc1 .Lmy_gfull_5
	v_readlane_b32 s2, v253, 37
	v_readlane_b32 s3, v250, 7
	v_readlane_b32 s8, v250, 0
	v_readlane_b32 s9, v250, 1
	s_lshl_b32 s2, s2, 12
	s_add_i32 s2, s2, 0x5000
	s_and_b32 s3, s3, 63
	s_lshl_b32 s3, s3, 6
	s_add_i32 s2, s2, s3
	s_add_u32 s8, s8, 0x70000
	s_addc_u32 s9, s9, 0
	v_mov_b32_e32 v0, s2
	v_mov_b32_e32 v1, 1
	s_waitcnt vmcnt(0) lgkmcnt(0)
	global_atomic_add v0, v1, s[8:9]
	buffer_inv sc1
	s_mov_b32 s2, 0
.Lmy_gspin_5:
	global_load_dword v2, v0, s[8:9] sc1
	s_waitcnt vmcnt(0)
	v_readfirstlane_b32 s3, v2
	s_cmp_ge_u32 s3, 4
	s_cbranch_scc1 .Lmy_gdone_5
	s_sleep 1
	s_add_i32 s2, s2, 1
	s_cmp_lt_u32 s2, 0x4000
	s_cbranch_scc1 .Lmy_gspin_5
.Lmy_gdone_5:
	s_branch .LBB0_2218
.Lmy_gfull_5:
	v_readlane_b32 s2, v252, 30
	s_waitcnt vmcnt(0) expcnt(0) lgkmcnt(0)
	s_nop 0
	v_mov_b32_e32 v0, s2
	ds_read_b32 v2, v0
	v_readlane_b32 s2, v252, 31
	s_waitcnt lgkmcnt(0)
	v_cmp_ne_u32_e32 vcc, 0, v2
	v_mov_b32_e32 v0, s2
	ds_read_b32 v0, v0
	s_cbranch_vccnz .LBB0_2182
	v_readlane_b32 s8, v250, 4
	v_readlane_b32 s9, v250, 5
	s_load_dwordx2 s[2:3], s[8:9], 0x4
	s_waitcnt lgkmcnt(0)
	s_mul_i32 s2, s2, s94
	s_mul_i32 s2, s2, s3
	s_mov_b32 s3, 1
	s_branch .LBB0_2170

.Lmy_gchk_1:
	s_mov_b32 s2, -1
	s_nop 0
	v_mbcnt_lo_u32_b32 v0, s2, 0
	v_mbcnt_hi_u32_b32 v0, s2, v0
	s_nop 0
	v_cmp_eq_u32_e32 vcc, 0, v0
	s_and_saveexec_b64 s[16:17], vcc
	s_cbranch_execz .LBB0_2303
	s_cmp_lg_u32 s101, 1
	s_cbranch_scc1 .Lmy_gfull_1
	v_readlane_b32 s2, v253, 37
	v_readlane_b32 s3, v250, 7
	v_readlane_b32 s8, v250, 0
	v_readlane_b32 s9, v250, 1
	s_lshl_b32 s2, s2, 12
	s_add_i32 s2, s2, 0x1000
	s_and_b32 s3, s3, 63
	s_lshl_b32 s3, s3, 6
	s_add_i32 s2, s2, s3
	s_add_u32 s8, s8, 0x70000
	s_addc_u32 s9, s9, 0
	v_mov_b32_e32 v0, s2
	v_mov_b32_e32 v1, 1
	s_waitcnt vmcnt(0) lgkmcnt(0)
	global_atomic_add v0, v1, s[8:9]
	buffer_inv sc1
	s_mov_b32 s2, 0
.Lmy_gspin_1:
	global_load_dword v2, v0, s[8:9] sc1
	s_waitcnt vmcnt(0)
	v_readfirstlane_b32 s3, v2
	s_cmp_ge_u32 s3, 4
	s_cbranch_scc1 .Lmy_gdone_1
	s_sleep 1
	s_add_i32 s2, s2, 1
	s_cmp_lt_u32 s2, 0x4000
	s_cbranch_scc1 .Lmy_gspin_1
.Lmy_gdone_1:
	s_branch .LBB0_2303
.Lmy_gfull_1:
	v_readlane_b32 s2, v252, 30
	s_waitcnt vmcnt(0) expcnt(0) lgkmcnt(0)
	s_nop 0
	v_mov_b32_e32 v0, s2
	ds_read_b32 v2, v0
	v_readlane_b32 s2, v252, 31
	s_waitcnt lgkmcnt(0)
	v_cmp_ne_u32_e32 vcc, 0, v2
	v_mov_b32_e32 v0, s2
	ds_read_b32 v0, v0
	s_cbranch_vccnz .LBB0_2267
	v_readlane_b32 s8, v250, 4
	v_readlane_b32 s9, v250, 5
	s_load_dwordx2 s[2:3], s[8:9], 0x4
	s_waitcnt lgkmcnt(0)
	s_mul_i32 s2, s2, s94
	s_mul_i32 s2, s2, s3
	s_mov_b32 s3, 1
	s_branch .LBB0_2255

.Lmy_gchk_2:
	s_mov_b32 s2, -1
	s_nop 0
	v_mbcnt_lo_u32_b32 v0, s2, 0
	v_mbcnt_hi_u32_b32 v0, s2, v0
	s_nop 0
	v_cmp_eq_u32_e32 vcc, 0, v0
	s_and_saveexec_b64 s[16:17], vcc
	s_cbranch_execz .LBB0_2381
	s_cmp_lg_u32 s101, 1
	s_cbranch_scc1 .Lmy_gfull_2
	v_readlane_b32 s2, v253, 37
	v_readlane_b32 s3, v250, 7
	v_readlane_b32 s8, v250, 0
	v_readlane_b32 s9, v250, 1
	s_lshl_b32 s2, s2, 12
	s_add_i32 s2, s2, 0x2000
	s_and_b32 s3, s3, 63
	s_lshl_b32 s3, s3, 6
	s_add_i32 s2, s2, s3
	s_add_u32 s8, s8, 0x70000
	s_addc_u32 s9, s9, 0
	v_mov_b32_e32 v0, s2
	v_mov_b32_e32 v1, 1
	s_waitcnt vmcnt(0) lgkmcnt(0)
	global_atomic_add v0, v1, s[8:9]
	buffer_inv sc1
	s_mov_b32 s2, 0
.Lmy_gspin_2:
	global_load_dword v2, v0, s[8:9] sc1
	s_waitcnt vmcnt(0)
	v_readfirstlane_b32 s3, v2
	s_cmp_ge_u32 s3, 4
	s_cbranch_scc1 .Lmy_gdone_2
	s_sleep 1
	s_add_i32 s2, s2, 1
	s_cmp_lt_u32 s2, 0x4000
	s_cbranch_scc1 .Lmy_gspin_2
.Lmy_gdone_2:
	s_branch .LBB0_2381
.Lmy_gfull_2:
	v_readlane_b32 s2, v252, 30
	s_waitcnt vmcnt(0) expcnt(0) lgkmcnt(0)
	s_nop 0
	v_mov_b32_e32 v0, s2
	ds_read_b32 v2, v0
	v_readlane_b32 s2, v252, 31
	s_waitcnt lgkmcnt(0)
	v_cmp_ne_u32_e32 vcc, 0, v2
	v_mov_b32_e32 v0, s2
	ds_read_b32 v0, v0
	s_cbranch_vccnz .LBB0_2345
	v_readlane_b32 s8, v250, 4
	v_readlane_b32 s9, v250, 5
	s_load_dwordx2 s[2:3], s[8:9], 0x4
	s_waitcnt lgkmcnt(0)
	s_mul_i32 s2, s2, s94
	s_mul_i32 s2, s2, s3
	s_mov_b32 s3, 1
	s_branch .LBB0_2333
